# GEMM K-loops: ds_reads before global loads, SADDR loads, B prefetch moved to phase start
# speedup vs baseline: 1.0057x; 1.0057x over previous
.LBB0_678:
	s_cmpk_lt_u32 s10, 0x3c0
	s_cselect_b64 s[66:67], -1, 0
	s_cmpk_gt_u32 s10, 0x3bf
	s_cselect_b64 s[52:53], -1, 0
	s_and_b64 vcc, exec, s[52:53]
	s_barrier
	s_waitcnt vmcnt(11)
	ds_write_b128 v215, v[98:101]
	s_waitcnt vmcnt(10)
	ds_write_b128 v215, v[102:105] offset:4096
	s_waitcnt vmcnt(9)
	ds_write_b128 v215, v[106:109] offset:8192
	s_waitcnt vmcnt(8)
	ds_write_b128 v215, v[110:113] offset:12288
	s_waitcnt vmcnt(7)
	ds_write_b128 v215, v[118:121] offset:16384
	s_waitcnt vmcnt(6)
	ds_write_b128 v215, v[122:125] offset:20480
	s_waitcnt vmcnt(5)
	ds_write_b128 v215, v[138:141] offset:24576
	s_waitcnt vmcnt(4)
	ds_write_b128 v215, v[142:145] offset:28672
	s_waitcnt vmcnt(3)
	ds_write_b128 v215, v[126:129] offset:32768
	s_waitcnt vmcnt(2)
	ds_write_b128 v215, v[130:133] offset:36864
	s_waitcnt vmcnt(1)
	ds_write_b128 v215, v[146:149] offset:40960
	s_waitcnt vmcnt(0)
	ds_write_b128 v215, v[150:153] offset:45056
	s_waitcnt lgkmcnt(0)
	s_barrier
	s_setprio 1
	v_add_u32_e32 v178, v214, v0
	ds_read_b128 v[194:197], v178 offset:32768
	ds_read_b128 v[198:201], v178 offset:34816
	ds_read_b128 v[218:221], v178 offset:36864
	ds_read_b128 v[238:241], v178 offset:38912
	v_add_u32_e32 v216, v213, v0
	ds_read_b128 v[178:181], v216
	ds_read_b128 v[182:185], v216 offset:2048
	ds_read_b128 v[186:189], v216 offset:4096
	ds_read_b128 v[190:193], v216 offset:6144
	s_cbranch_vccnz .LBB0_680
	s_add_u32 s100, s38, 0x1c3c000
	s_addc_u32 s101, s39, 0
	global_load_dwordx4 v[98:101], v208, s[100:101] offset:128
	v_add_u32_e32 v102, 0x10000, v208
	global_load_dwordx4 v[102:105], v102, s[100:101] offset:128
	v_add_u32_e32 v106, 0x20000, v208
	global_load_dwordx4 v[106:109], v106, s[100:101] offset:128
	v_add_u32_e32 v110, 0x30000, v208
	global_load_dwordx4 v[110:113], v110, s[100:101] offset:128
	v_add_u32_e32 v118, 0x40000, v208
	global_load_dwordx4 v[118:121], v118, s[100:101] offset:128
	v_add_u32_e32 v122, 0x50000, v208
	global_load_dwordx4 v[122:125], v122, s[100:101] offset:128
	v_add_u32_e32 v138, 0x60000, v208
	global_load_dwordx4 v[138:141], v138, s[100:101] offset:128
	v_add_u32_e32 v142, 0x70000, v208
	global_load_dwordx4 v[142:145], v142, s[100:101] offset:128
	s_add_u32 s100, s40, 0xac3c000
	s_addc_u32 s101, s41, 0
	global_load_dwordx4 v[126:129], v208, s[100:101] offset:128
	v_add_u32_e32 v130, 0x10000, v208
	global_load_dwordx4 v[130:133], v130, s[100:101] offset:128
	v_add_u32_e32 v146, 0x20000, v208
	global_load_dwordx4 v[146:149], v146, s[100:101] offset:128
	v_add_u32_e32 v150, 0x30000, v208
	global_load_dwordx4 v[150:153], v150, s[100:101] offset:128
.LBB0_680:
	s_waitcnt lgkmcnt(3)
	v_mfma_f32_16x16x32_bf16 v[174:177], v[178:181], v[194:197], v[174:177]
	v_mfma_f32_16x16x32_bf16 v[170:173], v[178:181], v[198:201], v[170:173]
	v_mfma_f32_16x16x32_bf16 v[166:169], v[178:181], v[218:221], v[166:169]
	v_mfma_f32_16x16x32_bf16 v[158:161], v[178:181], v[238:241], v[158:161]
	ds_read_b128 v[202:205], v216 offset:8192
	s_waitcnt lgkmcnt(3)
	v_mfma_f32_16x16x32_bf16 v[162:165], v[182:185], v[194:197], v[162:165]
	v_mfma_f32_16x16x32_bf16 v[154:157], v[182:185], v[198:201], v[154:157]
	v_mfma_f32_16x16x32_bf16 v[134:137], v[182:185], v[218:221], v[134:137]
	v_mfma_f32_16x16x32_bf16 v[114:117], v[182:185], v[238:241], v[114:117]
	v_add_u32_e32 v217, v214, v212
	ds_read_b128 v[242:245], v216 offset:10240
	ds_read_b128 v[178:181], v217 offset:32768
	s_waitcnt lgkmcnt(4)
	v_mfma_f32_16x16x32_bf16 v[94:97], v[186:189], v[194:197], v[94:97]
	v_mfma_f32_16x16x32_bf16 v[90:93], v[186:189], v[198:201], v[90:93]
	v_mfma_f32_16x16x32_bf16 v[86:89], v[186:189], v[218:221], v[86:89]
	v_mfma_f32_16x16x32_bf16 v[82:85], v[186:189], v[238:241], v[82:85]
	ds_read_b128 v[246:249], v216 offset:12288
	ds_read_b128 v[182:185], v217 offset:34816
	s_waitcnt lgkmcnt(5)
	v_mfma_f32_16x16x32_bf16 v[78:81], v[190:193], v[194:197], v[78:81]
	v_mfma_f32_16x16x32_bf16 v[74:77], v[190:193], v[198:201], v[74:77]
	v_mfma_f32_16x16x32_bf16 v[70:73], v[190:193], v[218:221], v[70:73]
	v_mfma_f32_16x16x32_bf16 v[66:69], v[190:193], v[238:241], v[66:69]
	ds_read_b128 v[226:229], v216 offset:14336
	ds_read_b128 v[186:189], v217 offset:36864
	s_waitcnt lgkmcnt(6)
	v_mfma_f32_16x16x32_bf16 v[62:65], v[202:205], v[194:197], v[62:65]
	v_mfma_f32_16x16x32_bf16 v[58:61], v[202:205], v[198:201], v[58:61]
	v_mfma_f32_16x16x32_bf16 v[54:57], v[202:205], v[218:221], v[54:57]
	v_mfma_f32_16x16x32_bf16 v[50:53], v[202:205], v[238:241], v[50:53]
	v_add_u32_e32 v216, v213, v212
	s_waitcnt lgkmcnt(5)
	v_mfma_f32_16x16x32_bf16 v[46:49], v[242:245], v[194:197], v[46:49]
	v_mfma_f32_16x16x32_bf16 v[42:45], v[242:245], v[198:201], v[42:45]
	v_mfma_f32_16x16x32_bf16 v[38:41], v[242:245], v[218:221], v[38:41]
	v_mfma_f32_16x16x32_bf16 v[34:37], v[242:245], v[238:241], v[34:37]
	ds_read_b128 v[242:245], v216
	ds_read_b128 v[190:193], v217 offset:38912
	ds_read_b128 v[202:205], v216 offset:2048
	s_waitcnt lgkmcnt(6)
	v_mfma_f32_16x16x32_bf16 v[30:33], v[246:249], v[194:197], v[30:33]
	v_mfma_f32_16x16x32_bf16 v[26:29], v[246:249], v[198:201], v[26:29]
	v_mfma_f32_16x16x32_bf16 v[18:21], v[246:249], v[218:221], v[18:21]
	v_mfma_f32_16x16x32_bf16 v[6:9], v[246:249], v[238:241], v[6:9]
	s_waitcnt lgkmcnt(4)
	v_mfma_f32_16x16x32_bf16 v[14:17], v[226:229], v[198:201], v[14:17]
	ds_read_b128 v[198:201], v216 offset:4096
	v_mfma_f32_16x16x32_bf16 v[22:25], v[226:229], v[194:197], v[22:25]
	v_mfma_f32_16x16x32_bf16 v[10:13], v[226:229], v[218:221], v[10:13]
	v_mfma_f32_16x16x32_bf16 v[2:5], v[226:229], v[238:241], v[2:5]
	ds_read_b128 v[194:197], v216 offset:6144
	s_waitcnt lgkmcnt(4)
	v_mfma_f32_16x16x32_bf16 v[174:177], v[242:245], v[178:181], v[174:177]
	v_mfma_f32_16x16x32_bf16 v[170:173], v[242:245], v[182:185], v[170:173]
	v_mfma_f32_16x16x32_bf16 v[166:169], v[242:245], v[186:189], v[166:169]
	s_waitcnt lgkmcnt(3)
	v_mfma_f32_16x16x32_bf16 v[158:161], v[242:245], v[190:193], v[158:161]
	s_branch .LBB0_677

.LBB0_1484:
	s_cmpk_lt_u32 s1, 0x3c0
	s_cselect_b64 s[50:51], -1, 0
	s_cmpk_gt_u32 s1, 0x3bf
	s_cselect_b64 s[44:45], -1, 0
	s_and_b64 vcc, exec, s[44:45]
	s_barrier
	s_waitcnt vmcnt(11)
	ds_write_b128 v215, v[98:101]
	s_waitcnt vmcnt(10)
	ds_write_b128 v215, v[102:105] offset:4096
	s_waitcnt vmcnt(9)
	ds_write_b128 v215, v[110:113] offset:8192
	s_waitcnt vmcnt(8)
	ds_write_b128 v215, v[114:117] offset:12288
	s_waitcnt vmcnt(7)
	ds_write_b128 v215, v[118:121] offset:16384
	s_waitcnt vmcnt(6)
	ds_write_b128 v215, v[130:133] offset:20480
	s_waitcnt vmcnt(5)
	ds_write_b128 v215, v[138:141] offset:24576
	s_waitcnt vmcnt(4)
	ds_write_b128 v215, v[146:149] offset:28672
	s_waitcnt vmcnt(3)
	ds_write_b128 v215, v[126:129] offset:32768
	s_waitcnt vmcnt(2)
	ds_write_b128 v215, v[134:137] offset:36864
	s_waitcnt vmcnt(1)
	ds_write_b128 v215, v[142:145] offset:40960
	s_waitcnt vmcnt(0)
	ds_write_b128 v215, v[150:153] offset:45056
	s_waitcnt lgkmcnt(0)
	s_barrier
	s_setprio 1
	v_add_u32_e32 v178, v214, v0
	ds_read_b128 v[194:197], v178 offset:32768
	ds_read_b128 v[198:201], v178 offset:34816
	ds_read_b128 v[218:221], v178 offset:36864
	ds_read_b128 v[226:229], v178 offset:38912
	v_add_u32_e32 v216, v213, v0
	ds_read_b128 v[178:181], v216
	ds_read_b128 v[182:185], v216 offset:2048
	ds_read_b128 v[186:189], v216 offset:4096
	ds_read_b128 v[190:193], v216 offset:6144
	s_cbranch_vccnz .LBB0_1486
	s_add_u32 s100, s38, 0x1c3c000
	s_addc_u32 s101, s39, 0
	global_load_dwordx4 v[98:101], v208, s[100:101] offset:128
	v_add_u32_e32 v102, 0x10000, v208
	global_load_dwordx4 v[102:105], v102, s[100:101] offset:128
	v_add_u32_e32 v110, 0x20000, v208
	global_load_dwordx4 v[110:113], v110, s[100:101] offset:128
	v_add_u32_e32 v114, 0x30000, v208
	global_load_dwordx4 v[114:117], v114, s[100:101] offset:128
	v_add_u32_e32 v118, 0x40000, v208
	global_load_dwordx4 v[118:121], v118, s[100:101] offset:128
	v_add_u32_e32 v130, 0x50000, v208
	global_load_dwordx4 v[130:133], v130, s[100:101] offset:128
	v_add_u32_e32 v138, 0x60000, v208
	global_load_dwordx4 v[138:141], v138, s[100:101] offset:128
	v_add_u32_e32 v146, 0x70000, v208
	global_load_dwordx4 v[146:149], v146, s[100:101] offset:128
	s_add_u32 s100, s40, 0xb34c000
	s_addc_u32 s101, s41, 0
	global_load_dwordx4 v[126:129], v208, s[100:101] offset:128
	v_add_u32_e32 v134, 0x10000, v208
	global_load_dwordx4 v[134:137], v134, s[100:101] offset:128
	v_add_u32_e32 v142, 0x20000, v208
	global_load_dwordx4 v[142:145], v142, s[100:101] offset:128
	v_add_u32_e32 v150, 0x30000, v208
	global_load_dwordx4 v[150:153], v150, s[100:101] offset:128
.LBB0_1486:
	s_waitcnt lgkmcnt(3)
	v_mfma_f32_16x16x32_bf16 v[174:177], v[178:181], v[194:197], v[174:177]
	v_mfma_f32_16x16x32_bf16 v[170:173], v[178:181], v[198:201], v[170:173]
	v_mfma_f32_16x16x32_bf16 v[166:169], v[178:181], v[218:221], v[166:169]
	v_mfma_f32_16x16x32_bf16 v[158:161], v[178:181], v[226:229], v[158:161]
	ds_read_b128 v[202:205], v216 offset:8192
	s_waitcnt lgkmcnt(3)
	v_mfma_f32_16x16x32_bf16 v[162:165], v[182:185], v[194:197], v[162:165]
	v_mfma_f32_16x16x32_bf16 v[154:157], v[182:185], v[198:201], v[154:157]
	v_mfma_f32_16x16x32_bf16 v[122:125], v[182:185], v[218:221], v[122:125]
	v_mfma_f32_16x16x32_bf16 v[106:109], v[182:185], v[226:229], v[106:109]
	v_add_u32_e32 v217, v214, v212
	ds_read_b128 v[238:241], v216 offset:10240
	ds_read_b128 v[178:181], v217 offset:32768
	s_waitcnt lgkmcnt(4)
	v_mfma_f32_16x16x32_bf16 v[94:97], v[186:189], v[194:197], v[94:97]
	v_mfma_f32_16x16x32_bf16 v[90:93], v[186:189], v[198:201], v[90:93]
	v_mfma_f32_16x16x32_bf16 v[86:89], v[186:189], v[218:221], v[86:89]
	v_mfma_f32_16x16x32_bf16 v[82:85], v[186:189], v[226:229], v[82:85]
	ds_read_b128 v[242:245], v216 offset:12288
	ds_read_b128 v[182:185], v217 offset:34816
	s_waitcnt lgkmcnt(5)
	v_mfma_f32_16x16x32_bf16 v[78:81], v[190:193], v[194:197], v[78:81]
	v_mfma_f32_16x16x32_bf16 v[74:77], v[190:193], v[198:201], v[74:77]
	v_mfma_f32_16x16x32_bf16 v[70:73], v[190:193], v[218:221], v[70:73]
	v_mfma_f32_16x16x32_bf16 v[66:69], v[190:193], v[226:229], v[66:69]
	ds_read_b128 v[246:249], v216 offset:14336
	ds_read_b128 v[186:189], v217 offset:36864
	s_waitcnt lgkmcnt(6)
	v_mfma_f32_16x16x32_bf16 v[62:65], v[202:205], v[194:197], v[62:65]
	v_mfma_f32_16x16x32_bf16 v[58:61], v[202:205], v[198:201], v[58:61]
	v_mfma_f32_16x16x32_bf16 v[54:57], v[202:205], v[218:221], v[54:57]
	v_mfma_f32_16x16x32_bf16 v[50:53], v[202:205], v[226:229], v[50:53]
	v_add_u32_e32 v216, v213, v212
	s_waitcnt lgkmcnt(5)
	v_mfma_f32_16x16x32_bf16 v[46:49], v[238:241], v[194:197], v[46:49]
	v_mfma_f32_16x16x32_bf16 v[42:45], v[238:241], v[198:201], v[42:45]
	v_mfma_f32_16x16x32_bf16 v[38:41], v[238:241], v[218:221], v[38:41]
	v_mfma_f32_16x16x32_bf16 v[34:37], v[238:241], v[226:229], v[34:37]
	ds_read_b128 v[238:241], v216
	ds_read_b128 v[190:193], v217 offset:38912
	ds_read_b128 v[202:205], v216 offset:2048
	s_waitcnt lgkmcnt(6)
	v_mfma_f32_16x16x32_bf16 v[30:33], v[242:245], v[194:197], v[30:33]
	v_mfma_f32_16x16x32_bf16 v[26:29], v[242:245], v[198:201], v[26:29]
	v_mfma_f32_16x16x32_bf16 v[18:21], v[242:245], v[218:221], v[18:21]
	v_mfma_f32_16x16x32_bf16 v[6:9], v[242:245], v[226:229], v[6:9]
	s_waitcnt lgkmcnt(4)
	v_mfma_f32_16x16x32_bf16 v[14:17], v[246:249], v[198:201], v[14:17]
	ds_read_b128 v[198:201], v216 offset:4096
	v_mfma_f32_16x16x32_bf16 v[22:25], v[246:249], v[194:197], v[22:25]
	v_mfma_f32_16x16x32_bf16 v[10:13], v[246:249], v[218:221], v[10:13]
	v_mfma_f32_16x16x32_bf16 v[2:5], v[246:249], v[226:229], v[2:5]
	ds_read_b128 v[194:197], v216 offset:6144
	s_waitcnt lgkmcnt(4)
	v_mfma_f32_16x16x32_bf16 v[174:177], v[238:241], v[178:181], v[174:177]
	v_mfma_f32_16x16x32_bf16 v[170:173], v[238:241], v[182:185], v[170:173]
	v_mfma_f32_16x16x32_bf16 v[166:169], v[238:241], v[186:189], v[166:169]
	s_waitcnt lgkmcnt(3)
	v_mfma_f32_16x16x32_bf16 v[158:161], v[238:241], v[190:193], v[158:161]
	s_branch .LBB0_1483

.LBB0_1682:
	s_add_i32 s1, s1, 64
	s_cmpk_lt_u32 s1, 0x3c0
	s_cselect_b64 s[40:41], -1, 0
	s_cmpk_gt_u32 s1, 0x3bf
	s_barrier
	s_waitcnt vmcnt(11)
	ds_write_b128 v216, v[2:5]
	s_waitcnt vmcnt(10)
	ds_write_b128 v216, v[6:9] offset:4096
	s_waitcnt vmcnt(9)
	ds_write_b128 v216, v[10:13] offset:8192
	s_waitcnt vmcnt(8)
	ds_write_b128 v216, v[14:17] offset:12288
	s_waitcnt vmcnt(7)
	ds_write_b128 v216, v[18:21] offset:16384
	s_waitcnt vmcnt(6)
	ds_write_b128 v216, v[26:29] offset:20480
	s_waitcnt vmcnt(5)
	ds_write_b128 v216, v[34:37] offset:24576
	s_waitcnt vmcnt(4)
	ds_write_b128 v216, v[42:45] offset:28672
	s_waitcnt vmcnt(3)
	ds_write_b128 v216, v[22:25] offset:32768
	s_waitcnt vmcnt(2)
	ds_write_b128 v216, v[30:33] offset:36864
	s_waitcnt vmcnt(1)
	ds_write_b128 v216, v[38:41] offset:40960
	s_waitcnt vmcnt(0)
	ds_write_b128 v216, v[46:49] offset:45056
	s_waitcnt lgkmcnt(0)
	s_barrier
	s_setprio 1
	v_add_u32_e32 v178, v215, v0
	ds_read_b128 v[194:197], v178 offset:32768
	ds_read_b128 v[198:201], v178 offset:34816
	ds_read_b128 v[218:221], v178 offset:36864
	ds_read_b128 v[226:229], v178 offset:38912
	v_add_u32_e32 v217, v214, v0
	ds_read_b128 v[178:181], v217
	ds_read_b128 v[182:185], v217 offset:2048
	ds_read_b128 v[186:189], v217 offset:4096
	ds_read_b128 v[190:193], v217 offset:6144
	s_cbranch_scc1 .LBB0_1684
	s_add_u32 s100, s36, 0x1c3b000
	s_addc_u32 s101, s37, 0
	global_load_dwordx4 v[2:5], v208, s[100:101] offset:2176
	v_add_u32_e32 v6, 0x10000, v208
	global_load_dwordx4 v[6:9], v6, s[100:101] offset:2176
	v_add_u32_e32 v10, 0x20000, v208
	global_load_dwordx4 v[10:13], v10, s[100:101] offset:2176
	v_add_u32_e32 v14, 0x30000, v208
	global_load_dwordx4 v[14:17], v14, s[100:101] offset:2176
	v_add_u32_e32 v18, 0x40000, v208
	global_load_dwordx4 v[18:21], v18, s[100:101] offset:2176
	v_add_u32_e32 v26, 0x50000, v208
	global_load_dwordx4 v[26:29], v26, s[100:101] offset:2176
	v_add_u32_e32 v34, 0x60000, v208
	global_load_dwordx4 v[34:37], v34, s[100:101] offset:2176
	v_add_u32_e32 v42, 0x70000, v208
	global_load_dwordx4 v[42:45], v42, s[100:101] offset:2176
	s_add_u32 s100, s38, 0xb54c000
	s_addc_u32 s101, s39, 0
	global_load_dwordx4 v[22:25], v208, s[100:101] offset:128
	v_add_u32_e32 v30, 0x10000, v208
	global_load_dwordx4 v[30:33], v30, s[100:101] offset:128
	v_add_u32_e32 v38, 0x20000, v208
	global_load_dwordx4 v[38:41], v38, s[100:101] offset:128
	v_add_u32_e32 v46, 0x30000, v208
	global_load_dwordx4 v[46:49], v46, s[100:101] offset:128
.LBB0_1684:
	s_waitcnt lgkmcnt(3)
	v_mfma_f32_16x16x32_bf16 v[114:117], v[178:181], v[194:197], v[114:117]
	v_mfma_f32_16x16x32_bf16 v[134:137], v[178:181], v[198:201], v[134:137]
	v_mfma_f32_16x16x32_bf16 v[138:141], v[178:181], v[218:221], v[138:141]
	v_mfma_f32_16x16x32_bf16 v[142:145], v[178:181], v[226:229], v[142:145]
	ds_read_b128 v[202:205], v217 offset:8192
	s_waitcnt lgkmcnt(3)
	v_mfma_f32_16x16x32_bf16 v[162:165], v[182:185], v[194:197], v[162:165]
	v_mfma_f32_16x16x32_bf16 v[166:169], v[182:185], v[198:201], v[166:169]
	v_mfma_f32_16x16x32_bf16 v[170:173], v[182:185], v[218:221], v[170:173]
	v_mfma_f32_16x16x32_bf16 v[174:177], v[182:185], v[226:229], v[174:177]
	v_add_u32_e32 v222, v215, v213
	ds_read_b128 v[238:241], v217 offset:10240
	ds_read_b128 v[178:181], v222 offset:32768
	s_waitcnt lgkmcnt(4)
	v_mfma_f32_16x16x32_bf16 v[146:149], v[186:189], v[194:197], v[146:149]
	v_mfma_f32_16x16x32_bf16 v[150:153], v[186:189], v[198:201], v[150:153]
	v_mfma_f32_16x16x32_bf16 v[154:157], v[186:189], v[218:221], v[154:157]
	v_mfma_f32_16x16x32_bf16 v[158:161], v[186:189], v[226:229], v[158:161]
	ds_read_b128 v[242:245], v217 offset:12288
	ds_read_b128 v[182:185], v222 offset:34816
	s_waitcnt lgkmcnt(5)
	v_mfma_f32_16x16x32_bf16 v[118:121], v[190:193], v[194:197], v[118:121]
	v_mfma_f32_16x16x32_bf16 v[122:125], v[190:193], v[198:201], v[122:125]
	v_mfma_f32_16x16x32_bf16 v[126:129], v[190:193], v[218:221], v[126:129]
	v_mfma_f32_16x16x32_bf16 v[130:133], v[190:193], v[226:229], v[130:133]
	ds_read_b128 v[246:249], v217 offset:14336
	ds_read_b128 v[186:189], v222 offset:36864
	s_waitcnt lgkmcnt(6)
	v_mfma_f32_16x16x32_bf16 v[98:101], v[202:205], v[194:197], v[98:101]
	v_mfma_f32_16x16x32_bf16 v[102:105], v[202:205], v[198:201], v[102:105]
	v_mfma_f32_16x16x32_bf16 v[106:109], v[202:205], v[218:221], v[106:109]
	v_mfma_f32_16x16x32_bf16 v[110:113], v[202:205], v[226:229], v[110:113]
	v_add_u32_e32 v217, v214, v213
	s_waitcnt lgkmcnt(5)
	v_mfma_f32_16x16x32_bf16 v[82:85], v[238:241], v[194:197], v[82:85]
	v_mfma_f32_16x16x32_bf16 v[86:89], v[238:241], v[198:201], v[86:89]
	v_mfma_f32_16x16x32_bf16 v[90:93], v[238:241], v[218:221], v[90:93]
	v_mfma_f32_16x16x32_bf16 v[94:97], v[238:241], v[226:229], v[94:97]
	ds_read_b128 v[238:241], v217
	ds_read_b128 v[190:193], v222 offset:38912
	ds_read_b128 v[202:205], v217 offset:2048
	s_waitcnt lgkmcnt(6)
	v_mfma_f32_16x16x32_bf16 v[66:69], v[242:245], v[194:197], v[66:69]
	v_mfma_f32_16x16x32_bf16 v[70:73], v[242:245], v[198:201], v[70:73]
	v_mfma_f32_16x16x32_bf16 v[74:77], v[242:245], v[218:221], v[74:77]
	v_mfma_f32_16x16x32_bf16 v[78:81], v[242:245], v[226:229], v[78:81]
	s_waitcnt lgkmcnt(4)
	v_mfma_f32_16x16x32_bf16 v[54:57], v[246:249], v[198:201], v[54:57]
	ds_read_b128 v[198:201], v217 offset:4096
	v_mfma_f32_16x16x32_bf16 v[50:53], v[246:249], v[194:197], v[50:53]
	v_mfma_f32_16x16x32_bf16 v[58:61], v[246:249], v[218:221], v[58:61]
	v_mfma_f32_16x16x32_bf16 v[62:65], v[246:249], v[226:229], v[62:65]
	ds_read_b128 v[194:197], v217 offset:6144
	s_waitcnt lgkmcnt(4)
	v_mfma_f32_16x16x32_bf16 v[114:117], v[238:241], v[178:181], v[114:117]
	v_mfma_f32_16x16x32_bf16 v[134:137], v[238:241], v[182:185], v[134:137]
	v_mfma_f32_16x16x32_bf16 v[138:141], v[238:241], v[186:189], v[138:141]
	s_waitcnt lgkmcnt(3)
	v_mfma_f32_16x16x32_bf16 v[142:145], v[238:241], v[190:193], v[142:145]
	s_branch .LBB0_1681

.LBB0_1815:
	s_cmpk_lt_u32 s20, 0xac0
	s_cselect_b64 s[42:43], -1, 0
	s_cmpk_gt_u32 s20, 0xabf
	s_cselect_b64 s[40:41], -1, 0
	s_and_b64 vcc, exec, s[40:41]
	s_barrier
	s_waitcnt vmcnt(11)
	ds_write_b128 v215, v[98:101]
	s_waitcnt vmcnt(10)
	ds_write_b128 v215, v[102:105] offset:4096
	s_waitcnt vmcnt(9)
	ds_write_b128 v215, v[110:113] offset:8192
	s_waitcnt vmcnt(8)
	ds_write_b128 v215, v[114:117] offset:12288
	s_waitcnt vmcnt(7)
	ds_write_b128 v215, v[122:125] offset:16384
	s_waitcnt vmcnt(6)
	ds_write_b128 v215, v[130:133] offset:20480
	s_waitcnt vmcnt(5)
	ds_write_b128 v215, v[138:141] offset:24576
	s_waitcnt vmcnt(4)
	ds_write_b128 v215, v[146:149] offset:28672
	s_waitcnt vmcnt(3)
	ds_write_b128 v215, v[126:129] offset:32768
	s_waitcnt vmcnt(2)
	ds_write_b128 v215, v[134:137] offset:36864
	s_waitcnt vmcnt(1)
	ds_write_b128 v215, v[142:145] offset:40960
	s_waitcnt vmcnt(0)
	ds_write_b128 v215, v[150:153] offset:45056
	s_waitcnt lgkmcnt(0)
	s_barrier
	s_setprio 1
	v_add_u32_e32 v178, v214, v0
	ds_read_b128 v[194:197], v178 offset:32768
	ds_read_b128 v[198:201], v178 offset:34816
	ds_read_b128 v[218:221], v178 offset:36864
	ds_read_b128 v[226:229], v178 offset:38912
	v_add_u32_e32 v216, v213, v0
	ds_read_b128 v[178:181], v216
	ds_read_b128 v[182:185], v216 offset:2048
	ds_read_b128 v[186:189], v216 offset:4096
	ds_read_b128 v[190:193], v216 offset:6144
	s_cbranch_vccnz .LBB0_1817
	s_add_u32 s100, s36, 0xc5cc000
	s_addc_u32 s101, s37, 0
	global_load_dwordx4 v[98:101], v208, s[100:101] offset:128
	v_add_u32_e32 v102, 0x2c000, v208
	global_load_dwordx4 v[102:105], v102, s[100:101] offset:128
	v_add_u32_e32 v110, 0x58000, v208
	global_load_dwordx4 v[110:113], v110, s[100:101] offset:128
	v_add_u32_e32 v114, 0x84000, v208
	global_load_dwordx4 v[114:117], v114, s[100:101] offset:128
	v_add_u32_e32 v122, 0xb0000, v208
	global_load_dwordx4 v[122:125], v122, s[100:101] offset:128
	v_add_u32_e32 v130, 0xdc000, v208
	global_load_dwordx4 v[130:133], v130, s[100:101] offset:128
	v_add_u32_e32 v138, 0x108000, v208
	global_load_dwordx4 v[138:141], v138, s[100:101] offset:128
	v_add_u32_e32 v146, 0x134000, v208
	global_load_dwordx4 v[146:149], v146, s[100:101] offset:128
	s_add_u32 s100, s38, 0xc04c000
	s_addc_u32 s101, s39, 0
	global_load_dwordx4 v[126:129], v208, s[100:101] offset:128
	v_add_u32_e32 v134, 0x2c000, v208
	global_load_dwordx4 v[134:137], v134, s[100:101] offset:128
	v_add_u32_e32 v142, 0x58000, v208
	global_load_dwordx4 v[142:145], v142, s[100:101] offset:128
	v_add_u32_e32 v150, 0x84000, v208
	global_load_dwordx4 v[150:153], v150, s[100:101] offset:128
.LBB0_1817:
	s_waitcnt lgkmcnt(3)
	v_mfma_f32_16x16x32_bf16 v[174:177], v[178:181], v[194:197], v[174:177]
	v_mfma_f32_16x16x32_bf16 v[170:173], v[178:181], v[198:201], v[170:173]
	v_mfma_f32_16x16x32_bf16 v[166:169], v[178:181], v[218:221], v[166:169]
	v_mfma_f32_16x16x32_bf16 v[158:161], v[178:181], v[226:229], v[158:161]
	ds_read_b128 v[202:205], v216 offset:8192
	s_waitcnt lgkmcnt(3)
	v_mfma_f32_16x16x32_bf16 v[162:165], v[182:185], v[194:197], v[162:165]
	v_mfma_f32_16x16x32_bf16 v[154:157], v[182:185], v[198:201], v[154:157]
	v_mfma_f32_16x16x32_bf16 v[118:121], v[182:185], v[218:221], v[118:121]
	v_mfma_f32_16x16x32_bf16 v[106:109], v[182:185], v[226:229], v[106:109]
	v_add_u32_e32 v217, v214, v212
	ds_read_b128 v[238:241], v216 offset:10240
	ds_read_b128 v[178:181], v217 offset:32768
	s_waitcnt lgkmcnt(4)
	v_mfma_f32_16x16x32_bf16 v[94:97], v[186:189], v[194:197], v[94:97]
	v_mfma_f32_16x16x32_bf16 v[90:93], v[186:189], v[198:201], v[90:93]
	v_mfma_f32_16x16x32_bf16 v[86:89], v[186:189], v[218:221], v[86:89]
	v_mfma_f32_16x16x32_bf16 v[82:85], v[186:189], v[226:229], v[82:85]
	ds_read_b128 v[242:245], v216 offset:12288
	ds_read_b128 v[182:185], v217 offset:34816
	s_waitcnt lgkmcnt(5)
	v_mfma_f32_16x16x32_bf16 v[78:81], v[190:193], v[194:197], v[78:81]
	v_mfma_f32_16x16x32_bf16 v[74:77], v[190:193], v[198:201], v[74:77]
	v_mfma_f32_16x16x32_bf16 v[70:73], v[190:193], v[218:221], v[70:73]
	v_mfma_f32_16x16x32_bf16 v[66:69], v[190:193], v[226:229], v[66:69]
	ds_read_b128 v[246:249], v216 offset:14336
	ds_read_b128 v[186:189], v217 offset:36864
	s_waitcnt lgkmcnt(6)
	v_mfma_f32_16x16x32_bf16 v[62:65], v[202:205], v[194:197], v[62:65]
	v_mfma_f32_16x16x32_bf16 v[58:61], v[202:205], v[198:201], v[58:61]
	v_mfma_f32_16x16x32_bf16 v[54:57], v[202:205], v[218:221], v[54:57]
	v_mfma_f32_16x16x32_bf16 v[50:53], v[202:205], v[226:229], v[50:53]
	v_add_u32_e32 v216, v213, v212
	s_waitcnt lgkmcnt(5)
	v_mfma_f32_16x16x32_bf16 v[46:49], v[238:241], v[194:197], v[46:49]
	v_mfma_f32_16x16x32_bf16 v[42:45], v[238:241], v[198:201], v[42:45]
	v_mfma_f32_16x16x32_bf16 v[38:41], v[238:241], v[218:221], v[38:41]
	v_mfma_f32_16x16x32_bf16 v[34:37], v[238:241], v[226:229], v[34:37]
	ds_read_b128 v[238:241], v216
	ds_read_b128 v[190:193], v217 offset:38912
	ds_read_b128 v[202:205], v216 offset:2048
	s_waitcnt lgkmcnt(6)
	v_mfma_f32_16x16x32_bf16 v[30:33], v[242:245], v[194:197], v[30:33]
	v_mfma_f32_16x16x32_bf16 v[26:29], v[242:245], v[198:201], v[26:29]
	v_mfma_f32_16x16x32_bf16 v[18:21], v[242:245], v[218:221], v[18:21]
	v_mfma_f32_16x16x32_bf16 v[6:9], v[242:245], v[226:229], v[6:9]
	s_waitcnt lgkmcnt(4)
	v_mfma_f32_16x16x32_bf16 v[14:17], v[246:249], v[198:201], v[14:17]
	ds_read_b128 v[198:201], v216 offset:4096
	v_mfma_f32_16x16x32_bf16 v[22:25], v[246:249], v[194:197], v[22:25]
	v_mfma_f32_16x16x32_bf16 v[10:13], v[246:249], v[218:221], v[10:13]
	v_mfma_f32_16x16x32_bf16 v[2:5], v[246:249], v[226:229], v[2:5]
	ds_read_b128 v[194:197], v216 offset:6144
	s_waitcnt lgkmcnt(4)
	v_mfma_f32_16x16x32_bf16 v[174:177], v[238:241], v[178:181], v[174:177]
	v_mfma_f32_16x16x32_bf16 v[170:173], v[238:241], v[182:185], v[170:173]
	v_mfma_f32_16x16x32_bf16 v[166:169], v[238:241], v[186:189], v[166:169]
	s_waitcnt lgkmcnt(3)
	v_mfma_f32_16x16x32_bf16 v[158:161], v[238:241], v[190:193], v[158:161]
	s_branch .LBB0_1814

	.amdhsa_kernel _Z4mega6Params
		.amdhsa_group_segment_fixed_size 16
		.amdhsa_private_segment_fixed_size 0
		.amdhsa_kernarg_size 512
		.amdhsa_user_sgpr_count 2
		.amdhsa_user_sgpr_dispatch_ptr 0
		.amdhsa_user_sgpr_queue_ptr 0
		.amdhsa_user_sgpr_kernarg_segment_ptr 1
		.amdhsa_user_sgpr_dispatch_id 0
		.amdhsa_user_sgpr_kernarg_preload_length 0
		.amdhsa_user_sgpr_kernarg_preload_offset 0
		.amdhsa_user_sgpr_private_segment_size 0
		.amdhsa_uses_dynamic_stack 0
		.amdhsa_enable_private_segment 0
		.amdhsa_system_sgpr_workgroup_id_x 1
		.amdhsa_system_sgpr_workgroup_id_y 0
		.amdhsa_system_sgpr_workgroup_id_z 0
		.amdhsa_system_sgpr_workgroup_info 0
		.amdhsa_system_vgpr_workitem_id 2
		.amdhsa_next_free_vgpr 256
		.amdhsa_next_free_sgpr 102
		.amdhsa_accum_offset 256
		.amdhsa_reserve_vcc 1
		.amdhsa_float_round_mode_32 0
		.amdhsa_float_round_mode_16_64 0
		.amdhsa_float_denorm_mode_32 3
		.amdhsa_float_denorm_mode_16_64 3
		.amdhsa_dx10_clamp 1
		.amdhsa_ieee_mode 1
		.amdhsa_fp16_overflow 0
		.amdhsa_tg_split 0
		.amdhsa_exception_fp_ieee_invalid_op 0
		.amdhsa_exception_fp_denorm_src 0
		.amdhsa_exception_fp_ieee_div_zero 0
		.amdhsa_exception_fp_ieee_overflow 0
		.amdhsa_exception_fp_ieee_underflow 0
		.amdhsa_exception_fp_ieee_inexact 0
		.amdhsa_exception_int_div_zero 0
	.end_amdhsa_kernel

amdhsa.kernels:
  - .agpr_count:     0
    .args:
      - .offset:         0
        .size:           256
        .value_kind:     by_value
      - .offset:         256
        .size:           4
        .value_kind:     hidden_block_count_x
      - .offset:         260
        .size:           4
        .value_kind:     hidden_block_count_y
      - .offset:         264
        .size:           4
        .value_kind:     hidden_block_count_z
      - .offset:         268
        .size:           2
        .value_kind:     hidden_group_size_x
      - .offset:         270
        .size:           2
        .value_kind:     hidden_group_size_y
      - .offset:         272
        .size:           2
        .value_kind:     hidden_group_size_z
      - .offset:         274
        .size:           2
        .value_kind:     hidden_remainder_x
      - .offset:         276
        .size:           2
        .value_kind:     hidden_remainder_y
      - .offset:         278
        .size:           2
        .value_kind:     hidden_remainder_z
      - .offset:         296
        .size:           8
        .value_kind:     hidden_global_offset_x
      - .offset:         304
        .size:           8
        .value_kind:     hidden_global_offset_y
      - .offset:         312
        .size:           8
        .value_kind:     hidden_global_offset_z
      - .offset:         320
        .size:           2
        .value_kind:     hidden_grid_dims
      - .offset:         344
        .size:           8
        .value_kind:     hidden_multigrid_sync_arg
      - .offset:         376
        .size:           4
        .value_kind:     hidden_dynamic_lds_size
    .group_segment_fixed_size: 16
    .kernarg_segment_align: 8
    .kernarg_segment_size: 512
    .language:       OpenCL C
    .language_version:
      - 2
      - 0
    .max_flat_workgroup_size: 256
    .name:           _Z4mega6Params
    .private_segment_fixed_size: 0
    .sgpr_count:     108
    .sgpr_spill_count: 244
    .symbol:         _Z4mega6Params.kd
    .uniform_work_group_size: 1
    .uses_dynamic_stack: false
    .vgpr_count:     256
    .vgpr_spill_count: 0
    .wavefront_size: 64
